# MLA PV: 14 of the 16 V^T fragment reads issued right after the QK MFMAs into phase-unused VGPRs (land under the softmax), last 2 at the PV head
# baseline (speedup 1.0000x reference)
; template <int DK, int MODE>
; __device__ __forceinline__ void attn_unit(const bf16_t* Q, int ldq, const bf16_t* K, int ldk, const bf16_t* V, int ldv, bf16_t* O, int ldo, int qb, char* shm, float sc) {
;     ...
;             float rm = fmaxf(max16(p0), max16(p1)); rm = xmax32(rm);
;             const float mn = fmaxf(mrun, rm), f = __builtin_amdgcn_exp2f(mrun - mn); mrun = mn;
; #pragma unroll
;             for (int r = 0; r < 16; ++r) { p0[r] = __builtin_amdgcn_exp2f(p0[r] - mn); p1[r] = __builtin_amdgcn_exp2f(p1[r] - mn); }
;             lrun = lrun * f + (sum16(p0) + sum16(p1));
; #pragma unroll
;             for (int r = 0; r < 16; ++r) { o[0][r] *= f; o[1][r] *= f; }
;         } else {
;             f32x16 om0, om1;
; #pragma unroll
;             for (int r = 0; r < 16; ++r) {
;                 const float e0 = __builtin_amdgcn_exp2f(-fmaxf(p0[r] * sc, -100.f)), e1 = __builtin_amdgcn_exp2f(-fmaxf(p1[r] * sc, -100.f));
;                 const float s0 = __builtin_amdgcn_rcpf(1.0f + e0), s1 = __builtin_amdgcn_rcpf(1.0f + e1);
;                 om0[r] = e0 * s0; om1[r] = e1 * s1; p0[r] = s0; p1[r] = s1;
;             }
;             if (diag) {
; #pragma unroll
;                 for (int r = 0; r < 16; ++r) { const int key = kbase + crow(r, hi);
;                     if (key >= qpos) { om0[r] = 1.f; p0[r] = 0.f; } if (key + 32 >= qpos) { om1[r] = 1.f; p1[r] = 0.f; } }
;             }
;             float gs[8], og[8];
; #pragma unroll
;             for (int g = 0; g < 4; ++g) { gs[g] = (om0[4 * g] * om0[4 * g + 1]) * (om0[4 * g + 2] * om0[4 * g + 3]); gs[4 + g] = (om1[4 * g] * om1[4 * g + 1]) * (om1[4 * g + 2] * om1[4 * g + 3]); }
; #pragma unroll
;             for (int g = 0; g < 8; ++g) og[g] = xother32(gs[g], hi);
;             float suf = lrun;
; #pragma unroll
;             for (int g = 7; g >= 0; --g) {
;                 const float T = suf * (hi == 0 ? og[g] : 1.f);
;                 f32x16& om = (g < 4) ? om0 : om1; f32x16& pp = (g < 4) ? p0 : p1; const int b = 4 * (g & 3);
;                 const float l3 = T, l2 = l3 * om[b + 3], l1 = l2 * om[b + 2], l0 = l1 * om[b + 1];
;                 pp[b + 3] *= l3; pp[b + 2] *= l2; pp[b + 1] *= l1; pp[b] *= l0;
;                 suf *= gs[g] * og[g];
;             }
;             lrun = suf;
;         }
;         pf[0] = packp(p0, 0); pf[1] = packp(p0, 8); pf[2] = packp(p1, 0); pf[3] = packp(p1, 8);
.LBB0_1359:
	v_max_f32_e32 v32, v49, v49
	v_max_f32_e32 v33, v48, v48
	v_max_f32_e32 v32, v33, v32
	v_max_f32_e32 v33, v51, v51
	v_max_f32_e32 v34, v50, v50
	v_max_f32_e32 v33, v34, v33
	v_max_f32_e32 v34, v55, v55
	v_max_f32_e32 v35, v54, v54
	v_max_f32_e32 v34, v35, v34
	v_max_f32_e32 v35, v57, v57
	v_max_f32_e32 v38, v56, v56
	v_max_f32_e32 v35, v38, v35
	v_max_f32_e32 v38, v59, v59
	v_max_f32_e32 v39, v58, v58
	v_max_f32_e32 v38, v39, v38
	v_max_f32_e32 v39, v63, v63
	v_max_f32_e32 v42, v62, v62
	v_max_f32_e32 v39, v42, v39
	v_max3_f32 v34, v52, v53, v34
	v_max3_f32 v39, v60, v61, v39
	v_max3_f32 v32, v32, v33, v34
	v_max3_f32 v33, v35, v38, v39
	v_max_f32_e32 v34, v41, v41
	v_max_f32_e32 v35, v40, v40
	v_max_f32_e32 v34, v35, v34
	v_max_f32_e32 v35, v47, v47
	v_max_f32_e32 v38, v46, v46
	v_max_f32_e32 v35, v38, v35
	v_max_f32_e32 v38, v133, v133
	v_max_f32_e32 v39, v132, v132
	v_max_f32_e32 v38, v39, v38
	v_max_f32_e32 v39, v131, v131
	v_max_f32_e32 v42, v130, v130
	v_max_f32_e32 v39, v42, v39
	v_max_f32_e32 v42, v127, v127
	v_max_f32_e32 v43, v126, v126
	v_max_f32_e32 v42, v43, v42
	v_max3_f32 v42, v128, v129, v42
	v_max3_f32 v34, v36, v37, v34
	v_max3_f32 v35, v44, v45, v35
	v_max3_f32 v38, v38, v39, v42
	v_max3_f32 v34, v34, v35, v38
	v_max3_f32 v32, v32, v33, v34
	v_mov_b32_e32 v33, v32
	s_nop 1
	v_permlane32_swap_b32_e32 v32, v33
	v_max3_f32 v143, v142, v32, v33
	v_sub_f32_e32 v32, v48, v143
	v_exp_f32_e32 v33, v32
	v_sub_f32_e32 v32, v36, v143
	v_sub_f32_e32 v34, v49, v143
	v_sub_f32_e32 v36, v50, v143
	v_exp_f32_e32 v35, v34
	v_sub_f32_e32 v34, v37, v143
	v_exp_f32_e32 v37, v36
	v_sub_f32_e32 v36, v40, v143
	v_sub_f32_e32 v38, v51, v143
	v_sub_f32_e32 v40, v52, v143
	v_exp_f32_e32 v39, v38
	v_sub_f32_e32 v38, v41, v143
	v_exp_f32_e32 v41, v40
	v_sub_f32_e32 v40, v44, v143
	v_sub_f32_e32 v42, v53, v143
	v_sub_f32_e32 v44, v54, v143
	v_exp_f32_e32 v43, v42
	v_sub_f32_e32 v42, v45, v143
	v_exp_f32_e32 v45, v44
	v_sub_f32_e32 v44, v46, v143
	v_sub_f32_e32 v46, v55, v143
	v_exp_f32_e32 v32, v32
	v_exp_f32_e32 v34, v34
	v_exp_f32_e32 v36, v36
	v_exp_f32_e32 v38, v38
	v_exp_f32_e32 v49, v46
	v_sub_f32_e32 v46, v47, v143
	v_exp_f32_e32 v40, v40
	v_exp_f32_e32 v42, v42
	v_exp_f32_e32 v44, v44
	v_exp_f32_e32 v48, v46
	v_sub_f32_e32 v46, v56, v143
	v_sub_f32_e32 v50, v57, v143
	v_sub_f32_e32 v52, v58, v143
	v_sub_f32_e32 v54, v59, v143
	v_exp_f32_e32 v47, v46
	v_sub_f32_e32 v46, v132, v143
	v_exp_f32_e32 v51, v50
	v_sub_f32_e32 v50, v133, v143
	v_exp_f32_e32 v53, v52
	v_sub_f32_e32 v52, v130, v143
	v_exp_f32_e32 v55, v54
	v_sub_f32_e32 v54, v131, v143
	v_sub_f32_e32 v56, v60, v143
	v_sub_f32_e32 v58, v61, v143
	v_sub_f32_e32 v60, v62, v143
	v_sub_f32_e32 v62, v63, v143
	v_exp_f32_e32 v46, v46
	v_exp_f32_e32 v50, v50
	v_exp_f32_e32 v52, v52
	v_exp_f32_e32 v54, v54
	v_exp_f32_e32 v57, v56
	v_sub_f32_e32 v56, v128, v143
	v_exp_f32_e32 v59, v58
	v_sub_f32_e32 v58, v129, v143
	v_exp_f32_e32 v61, v60
	v_sub_f32_e32 v60, v126, v143
	v_exp_f32_e32 v63, v62
	v_sub_f32_e32 v62, v127, v143
	v_exp_f32_e32 v56, v56
	v_exp_f32_e32 v58, v58
	v_exp_f32_e32 v60, v60
	v_exp_f32_e32 v62, v62
	v_pk_add_f32 v[126:127], v[32:33], v[34:35]
	v_pk_add_f32 v[130:131], v[36:37], v[38:39]
	v_pk_add_f32 v[132:133], v[44:45], v[48:49]
	v_pk_add_f32 v[126:127], v[126:127], v[130:131]
	v_pk_add_f32 v[130:131], v[40:41], v[42:43]
	v_sub_f32_e32 v142, v142, v143
	v_pk_add_f32 v[130:131], v[130:131], v[132:133]
	v_pk_add_f32 v[132:133], v[52:53], v[54:55]
	v_pk_add_f32 v[126:127], v[126:127], v[130:131]
	v_pk_add_f32 v[130:131], v[46:47], v[50:51]
	v_pk_add_f32 v[144:145], v[60:61], v[62:63]
	v_pk_add_f32 v[130:131], v[130:131], v[132:133]
	v_pk_add_f32 v[132:133], v[56:57], v[58:59]
	v_exp_f32_e32 v128, v142
	v_pk_add_f32 v[132:133], v[132:133], v[144:145]
	v_mov_b32_e32 v142, v143
	v_pk_add_f32 v[130:131], v[130:131], v[132:133]
	v_pk_mul_f32 v[30:31], v[30:31], v[128:129] op_sel_hi:[1,0]
	v_pk_add_f32 v[126:127], v[126:127], v[130:131]
	v_pk_mul_f32 v[28:29], v[28:29], v[128:129] op_sel_hi:[1,0]
	v_add_f32_e32 v126, v126, v127
	v_fmac_f32_e32 v126, v141, v128
	v_pk_mul_f32 v[26:27], v[26:27], v[128:129] op_sel_hi:[1,0]
	v_pk_mul_f32 v[24:25], v[24:25], v[128:129] op_sel_hi:[1,0]
	v_pk_mul_f32 v[22:23], v[22:23], v[128:129] op_sel_hi:[1,0]
	v_pk_mul_f32 v[20:21], v[20:21], v[128:129] op_sel_hi:[1,0]
	v_pk_mul_f32 v[18:19], v[18:19], v[128:129] op_sel_hi:[1,0]
	v_pk_mul_f32 v[16:17], v[16:17], v[128:129] op_sel_hi:[1,0]
	v_pk_mul_f32 v[14:15], v[14:15], v[128:129] op_sel_hi:[1,0]
	v_pk_mul_f32 v[12:13], v[12:13], v[128:129] op_sel_hi:[1,0]
	v_pk_mul_f32 v[10:11], v[10:11], v[128:129] op_sel_hi:[1,0]
	v_pk_mul_f32 v[8:9], v[8:9], v[128:129] op_sel_hi:[1,0]
	v_pk_mul_f32 v[6:7], v[6:7], v[128:129] op_sel_hi:[1,0]
	v_pk_mul_f32 v[4:5], v[4:5], v[128:129] op_sel_hi:[1,0]
	v_pk_mul_f32 v[2:3], v[2:3], v[128:129] op_sel_hi:[1,0]
	v_pk_mul_f32 v[0:1], v[0:1], v[128:129] op_sel_hi:[1,0]
	v_cvt_pk_bf16_f32 v128, v33, v35
	v_cvt_pk_bf16_f32 v129, v37, v39
	v_cvt_pk_bf16_f32 v130, v41, v43
	v_cvt_pk_bf16_f32 v131, v45, v49
	v_cvt_pk_bf16_f32 v144, v47, v51
	v_cvt_pk_bf16_f32 v145, v53, v55
	v_cvt_pk_bf16_f32 v146, v57, v59
	v_cvt_pk_bf16_f32 v147, v61, v63
	v_cvt_pk_bf16_f32 v32, v32, v34
	v_cvt_pk_bf16_f32 v33, v36, v38
	v_cvt_pk_bf16_f32 v34, v40, v42
	v_cvt_pk_bf16_f32 v35, v44, v48
	v_add_u32_e32 v44, v135, v136
	v_cvt_pk_bf16_f32 v36, v46, v50
	v_cvt_pk_bf16_f32 v37, v52, v54
	v_cvt_pk_bf16_f32 v38, v56, v58
	v_cvt_pk_bf16_f32 v39, v60, v62
	s_waitcnt lgkmcnt(0)
	ds_read_b64_tr_b16 v[226:227], v44 offset:41984
	ds_read_b64_tr_b16 v[228:229], v44 offset:42496
	v_mov_b32_e32 v141, v126
	v_mfma_f32_32x32x16_bf16 v[16:31], v[196:199], v[128:131], v[16:31]
	v_mfma_f32_32x32x16_bf16 v[16:31], v[200:203], v[144:147], v[16:31]
	v_mfma_f32_32x32x16_bf16 v[16:31], v[204:207], v[32:35], v[16:31]
	v_mfma_f32_32x32x16_bf16 v[16:31], v[210:213], v[36:39], v[16:31]
	v_mfma_f32_32x32x16_bf16 v[0:15], v[214:217], v[128:131], v[0:15]
	v_mfma_f32_32x32x16_bf16 v[0:15], v[218:221], v[144:147], v[0:15]
	v_mfma_f32_32x32x16_bf16 v[0:15], v[222:225], v[32:35], v[0:15]
	s_waitcnt lgkmcnt(0)
	v_mfma_f32_32x32x16_bf16 v[0:15], v[226:229], v[36:39], v[0:15]

; __device__ __forceinline__ int crow(int r, int hi) { return (r & 3) + 8 * (r >> 2) + 4 * hi; }
; __device__ __forceinline__ s16x4 vtr(lds_cptr p) { return __builtin_bit_cast(s16x4, __builtin_amdgcn_ds_read_tr16_b64_v4i16((ATT_LAS s16x4*)p)); }
; template <int KEYS> __device__ __forceinline__ void pv_tile(f32x16 (&o)[2], lds_cptr vbase, const bf16x8 (&pf)[KEYS / 16], int lane) {
;     const int hi = lane >> 5, li = lane & 15;
;     lds_cptr vp = vbase + (4 * hi + (li >> 2)) * 64 + ((lane >> 4) & 1) * 32 + (lane & 3) * 8;
; #pragma unroll
;     for (int d0 = 0; d0 < 2; ++d0)
; #pragma unroll
;         for (int ks = 0; ks < KEYS / 16; ++ks) {
;             const s16x4 lo = vtr(vp + d0 * (KEYS * 64) + ks * 1024), hh = vtr(vp + d0 * (KEYS * 64) + ks * 1024 + 512);
; template <int DK, int MODE>
; __device__ __forceinline__ void attn_unit(const bf16_t* Q, int ldq, const bf16_t* K, int ldk, const bf16_t* V, int ldv, bf16_t* O, int ldo, int qb, char* shm, float sc) {
;     ...
;     auto att_compute = [&](int it, int tt, char* buf) __attribute__((always_inline)) {
;         const int kbase = tt * 64;
;         bool active = !(kbase > qb * 256 + wid * 32 + 31);
;         if (MODE == 1) active = active && (wminR < SB_SAT);
;         if (active) {
;         f32x16 p0 = f32x16{}, p1 = f32x16{};
;         const char* kp = buf + r32 * L::KS + hi * 16;
; #pragma unroll
;         for (int s = 0; s < NS; ++s) {
;             const bf16x8 a0 = *(const bf16x8*)(kp + s * 32), a1 = *(const bf16x8*)(kp + 32 * L::KS + s * 32);
;             p0 = __builtin_amdgcn_mfma_f32_32x32x16_bf16(a0, qf[s], p0, 0, 0, 0);
;             p1 = __builtin_amdgcn_mfma_f32_32x32x16_bf16(a1, qf[s], p1, 0, 0, 0);
;         }
;         const bool diag = (kbase + 63 >= qb * 256 + wid * 32);
;         bf16x8 pf[4];
;         if (MODE == 0) {
; #pragma unroll
;             for (int r = 0; r < 16; ++r) { p0[r] *= sc; p1[r] *= sc; }
;             if (diag) {
; #pragma unroll
;                 for (int r = 0; r < 16; ++r) { const int key = kbase + crow(r, hi); if (key > qpos) p0[r] = -INFINITY; if (key + 32 > qpos) p1[r] = -INFINITY; }
.LBB0_1365:
	s_or_b64 exec, exec, s[28:29]
	v_lshl_add_u64 v[32:33], s[0:1], 0, v[118:119]
	v_lshlrev_b64 v[32:33], 10, v[32:33]
	v_lshl_add_u64 v[32:33], v[122:123], 0, v[32:33]
	global_load_dwordx4 v[100:103], v[32:33], off
	s_sub_i32 s0, s31, 63
	s_cmp_gt_i32 s0, s30
	s_cbranch_scc1 .LBB0_1369
	ds_read_b128 v[148:151], v140
	ds_read_b128 v[152:155], v140 offset:6656
	ds_read_b128 v[156:159], v140 offset:32
	ds_read_b128 v[160:163], v140 offset:6688
	ds_read_b128 v[164:167], v140 offset:64
	ds_read_b128 v[168:171], v140 offset:6720
	ds_read_b128 v[172:175], v140 offset:96
	ds_read_b128 v[176:179], v140 offset:6752
	ds_read_b128 v[180:183], v140 offset:128
	ds_read_b128 v[184:187], v140 offset:6784
	ds_read_b128 v[188:191], v140 offset:160
	ds_read_b128 v[192:195], v140 offset:6816
	s_cmp_lt_i32 s31, s9
	s_waitcnt lgkmcnt(11)
	v_mfma_f32_32x32x16_bf16 v[48:63], v[148:151], v[64:67], 0
	s_waitcnt lgkmcnt(10)
	v_mfma_f32_32x32x16_bf16 v[32:47], v[152:155], v[64:67], 0
	s_waitcnt lgkmcnt(9)
	v_mfma_f32_32x32x16_bf16 v[48:63], v[156:159], v[68:71], v[48:63]
	s_waitcnt lgkmcnt(8)
	v_mfma_f32_32x32x16_bf16 v[32:47], v[160:163], v[68:71], v[32:47]
	s_waitcnt lgkmcnt(7)
	v_mfma_f32_32x32x16_bf16 v[48:63], v[164:167], v[72:75], v[48:63]
	s_waitcnt lgkmcnt(6)
	v_mfma_f32_32x32x16_bf16 v[32:47], v[168:171], v[72:75], v[32:47]
	s_waitcnt lgkmcnt(5)
	v_mfma_f32_32x32x16_bf16 v[48:63], v[172:175], v[76:79], v[48:63]
	s_waitcnt lgkmcnt(4)
	v_mfma_f32_32x32x16_bf16 v[32:47], v[176:179], v[76:79], v[32:47]
	s_waitcnt lgkmcnt(3)
	v_mfma_f32_32x32x16_bf16 v[48:63], v[180:183], v[80:83], v[48:63]
	s_waitcnt lgkmcnt(2)
	v_mfma_f32_32x32x16_bf16 v[32:47], v[184:187], v[80:83], v[32:47]
	s_waitcnt lgkmcnt(1)
	v_mfma_f32_32x32x16_bf16 v[48:63], v[188:191], v[84:87], v[48:63]
	s_waitcnt lgkmcnt(0)
	v_mfma_f32_32x32x16_bf16 v[32:47], v[192:195], v[84:87], v[32:47]
	v_add_u32_e32 v230, v135, v136
	ds_read_b64_tr_b16 v[196:197], v230 offset:13312
	ds_read_b64_tr_b16 v[198:199], v230 offset:13824
	ds_read_b64_tr_b16 v[200:201], v230 offset:14336
	ds_read_b64_tr_b16 v[202:203], v230 offset:14848
	ds_read_b64_tr_b16 v[204:205], v230 offset:15360
	ds_read_b64_tr_b16 v[206:207], v230 offset:15872
	ds_read_b64_tr_b16 v[210:211], v230 offset:16384
	ds_read_b64_tr_b16 v[212:213], v230 offset:16896
	ds_read_b64_tr_b16 v[214:215], v230 offset:17408
	ds_read_b64_tr_b16 v[216:217], v230 offset:17920
	ds_read_b64_tr_b16 v[218:219], v230 offset:18432
	ds_read_b64_tr_b16 v[220:221], v230 offset:18944
	ds_read_b64_tr_b16 v[222:223], v230 offset:19456
	ds_read_b64_tr_b16 v[224:225], v230 offset:19968
	s_nop 9
	v_mul_f32_e64 v62, v62, s24
	v_mul_f32_e64 v63, v63, s24
	v_mul_f32_e64 v60, v60, s24
	v_mul_f32_e64 v61, v61, s24
	v_mul_f32_e64 v58, v58, s24
	v_mul_f32_e64 v59, v59, s24
	v_pk_mul_f32 v[56:57], v[56:57], s[24:25] op_sel_hi:[1,0]
	v_pk_mul_f32 v[54:55], v[54:55], s[24:25] op_sel_hi:[1,0]
	v_pk_mul_f32 v[52:53], v[52:53], s[24:25] op_sel_hi:[1,0]
	v_pk_mul_f32 v[50:51], v[50:51], s[24:25] op_sel_hi:[1,0]
	v_pk_mul_f32 v[48:49], v[48:49], s[24:25] op_sel_hi:[1,0]
	v_pk_mul_f32 v[126:127], v[46:47], s[24:25] op_sel_hi:[1,0]
	v_pk_mul_f32 v[128:129], v[44:45], s[24:25] op_sel_hi:[1,0]
	v_pk_mul_f32 v[130:131], v[42:43], s[24:25] op_sel_hi:[1,0]
	v_pk_mul_f32 v[132:133], v[40:41], s[24:25] op_sel_hi:[1,0]
	v_pk_mul_f32 v[46:47], v[38:39], s[24:25] op_sel_hi:[1,0]
	v_pk_mul_f32 v[44:45], v[36:37], s[24:25] op_sel_hi:[1,0]
	v_pk_mul_f32 v[40:41], v[34:35], s[24:25] op_sel_hi:[1,0]
	v_pk_mul_f32 v[36:37], v[32:33], s[24:25] op_sel_hi:[1,0]
	s_cbranch_scc1 .LBB0_1368
	v_add_u32_e32 v32, s31, v134
	v_subrev_u32_e32 v34, 31, v32
	v_subrev_u32_e32 v33, 63, v32
	v_cmp_le_i32_e32 vcc, v34, v112
	s_nop 1
	v_cndmask_b32_e32 v36, v243, v36, vcc
	v_cmp_lt_i32_e32 vcc, v33, v112
	s_nop 1
	v_cndmask_b32_e32 v49, v243, v49, vcc
	v_cmp_le_i32_e32 vcc, v33, v112
	v_subrev_u32_e32 v33, 30, v32
	s_nop 0
	v_cndmask_b32_e32 v48, v243, v48, vcc
	v_cmp_le_i32_e32 vcc, v33, v112
	v_subrev_u32_e32 v33, 61, v32
	s_nop 0
	v_cndmask_b32_e32 v37, v243, v37, vcc
	v_cmp_le_i32_e32 vcc, v33, v112
	v_subrev_u32_e32 v33, 29, v32
	s_nop 0
	v_cndmask_b32_e32 v50, v243, v50, vcc
	v_cmp_le_i32_e32 vcc, v33, v112
	v_subrev_u32_e32 v33, 60, v32
	s_nop 0
	v_cndmask_b32_e32 v40, v243, v40, vcc
	v_cmp_le_i32_e32 vcc, v33, v112
	v_subrev_u32_e32 v33, 28, v32
	s_nop 0
	v_cndmask_b32_e32 v51, v243, v51, vcc
	v_cmp_le_i32_e32 vcc, v33, v112
	v_subrev_u32_e32 v33, 55, v32
	s_nop 0
	v_cndmask_b32_e32 v41, v243, v41, vcc
	v_cmp_le_i32_e32 vcc, v33, v112
	v_subrev_u32_e32 v33, 23, v32
	s_nop 0
	v_cndmask_b32_e32 v52, v243, v52, vcc
	v_cmp_le_i32_e32 vcc, v33, v112
	v_subrev_u32_e32 v33, 54, v32
	s_nop 0
	v_cndmask_b32_e32 v44, v243, v44, vcc
	v_cmp_le_i32_e32 vcc, v33, v112
	v_subrev_u32_e32 v33, 22, v32
	s_nop 0
	v_cndmask_b32_e32 v53, v243, v53, vcc
	v_cmp_le_i32_e32 vcc, v33, v112
	v_subrev_u32_e32 v33, 53, v32
	s_nop 0
	v_cndmask_b32_e32 v45, v243, v45, vcc
	v_cmp_le_i32_e32 vcc, v33, v112
	v_subrev_u32_e32 v33, 21, v32
	s_nop 0
	v_cndmask_b32_e32 v54, v243, v54, vcc
	v_cmp_le_i32_e32 vcc, v33, v112
	v_subrev_u32_e32 v33, 52, v32
	s_nop 0
	v_cndmask_b32_e32 v46, v243, v46, vcc
	v_cmp_le_i32_e32 vcc, v33, v112
	v_subrev_u32_e32 v33, 20, v32
	s_nop 0
	v_cndmask_b32_e32 v55, v243, v55, vcc
	v_cmp_le_i32_e32 vcc, v33, v112
	v_subrev_u32_e32 v33, 47, v32
	s_nop 0
	v_cndmask_b32_e32 v47, v243, v47, vcc
	v_cmp_le_i32_e32 vcc, v33, v112
	v_add_u32_e32 v33, -15, v32
	s_nop 0
	v_cndmask_b32_e32 v56, v243, v56, vcc
	v_cmp_le_i32_e32 vcc, v33, v112
	v_subrev_u32_e32 v33, 46, v32
	s_nop 0
	v_cndmask_b32_e32 v132, v243, v132, vcc
; __device__ __forceinline__ int crow(int r, int hi) { return (r & 3) + 8 * (r >> 2) + 4 * hi; }
; template <int DK, int MODE>
; __device__ __forceinline__ void attn_unit(const bf16_t* Q, int ldq, const bf16_t* K, int ldk, const bf16_t* V, int ldv, bf16_t* O, int ldo, int qb, char* shm, float sc) {
;     ...
;             if (diag) {
; #pragma unroll
;                 for (int r = 0; r < 16; ++r) { const int key = kbase + crow(r, hi); if (key > qpos) p0[r] = -INFINITY; if (key + 32 > qpos) p1[r] = -INFINITY; }
;             }
	v_cmp_le_i32_e32 vcc, v33, v112
	v_add_u32_e32 v33, -14, v32
	s_nop 0
	v_cndmask_b32_e32 v57, v243, v57, vcc
	v_cmp_le_i32_e32 vcc, v33, v112
	v_subrev_u32_e32 v33, 45, v32
	s_nop 0
	v_cndmask_b32_e32 v133, v243, v133, vcc
	v_cmp_le_i32_e32 vcc, v33, v112
	v_add_u32_e32 v33, -13, v32
	s_nop 0
	v_cndmask_b32_e32 v58, v243, v58, vcc
	v_cmp_le_i32_e32 vcc, v33, v112
	v_subrev_u32_e32 v33, 44, v32
	s_nop 0
	v_cndmask_b32_e32 v130, v243, v130, vcc
	v_cmp_le_i32_e32 vcc, v33, v112
	v_add_u32_e32 v33, -12, v32
	s_nop 0
	v_cndmask_b32_e32 v59, v243, v59, vcc
	v_cmp_le_i32_e32 vcc, v33, v112
	v_subrev_u32_e32 v33, 39, v32
	s_nop 0
	v_cndmask_b32_e32 v131, v243, v131, vcc
	v_cmp_le_i32_e32 vcc, v33, v112
	v_add_u32_e32 v33, -7, v32
	s_nop 0
	v_cndmask_b32_e32 v60, v243, v60, vcc
	v_cmp_le_i32_e32 vcc, v33, v112
	v_subrev_u32_e32 v33, 38, v32
	s_nop 0
	v_cndmask_b32_e32 v128, v243, v128, vcc
	v_cmp_le_i32_e32 vcc, v33, v112
	v_add_u32_e32 v33, -6, v32
	s_nop 0
	v_cndmask_b32_e32 v61, v243, v61, vcc
	v_cmp_le_i32_e32 vcc, v33, v112
	v_subrev_u32_e32 v33, 37, v32
	s_nop 0
	v_cndmask_b32_e32 v129, v243, v129, vcc
	v_cmp_le_i32_e32 vcc, v33, v112
	v_add_u32_e32 v33, -5, v32
	s_nop 0
	v_cndmask_b32_e32 v62, v243, v62, vcc
	v_cmp_le_i32_e32 vcc, v33, v112
	v_subrev_u32_e32 v33, 36, v32
	v_add_u32_e32 v32, -4, v32
	v_cndmask_b32_e32 v126, v243, v126, vcc
	v_cmp_le_i32_e32 vcc, v33, v112
	s_nop 1
	v_cndmask_b32_e32 v63, v243, v63, vcc
	v_cmp_le_i32_e32 vcc, v32, v112
	s_nop 1
	v_cndmask_b32_e32 v127, v243, v127, vcc
; template <int DK, int MODE>
; __device__ __forceinline__ void attn_unit(const bf16_t* Q, int ldq, const bf16_t* K, int ldk, const bf16_t* V, int ldv, bf16_t* O, int ldo, int qb, char* shm, float sc) {
;     ...
;             float rm = fmaxf(max16(p0), max16(p1)); rm = xmax32(rm);
;             const float mn = fmaxf(mrun, rm), f = __builtin_amdgcn_exp2f(mrun - mn); mrun = mn;
; #pragma unroll
;             for (int r = 0; r < 16; ++r) { p0[r] = __builtin_amdgcn_exp2f(p0[r] - mn); p1[r] = __builtin_amdgcn_exp2f(p1[r] - mn); }
;             lrun = lrun * f + (sum16(p0) + sum16(p1));
; #pragma unroll
;             for (int r = 0; r < 16; ++r) { o[0][r] *= f; o[1][r] *= f; }
;         } else {
;             f32x16 om0, om1;
; #pragma unroll
;             for (int r = 0; r < 16; ++r) {
;                 const float e0 = __builtin_amdgcn_exp2f(-fmaxf(p0[r] * sc, -100.f)), e1 = __builtin_amdgcn_exp2f(-fmaxf(p1[r] * sc, -100.f));
;                 const float s0 = __builtin_amdgcn_rcpf(1.0f + e0), s1 = __builtin_amdgcn_rcpf(1.0f + e1);
;                 om0[r] = e0 * s0; om1[r] = e1 * s1; p0[r] = s0; p1[r] = s1;
;             }
;             if (diag) {
; #pragma unroll
;                 for (int r = 0; r < 16; ++r) { const int key = kbase + crow(r, hi);
;                     if (key >= qpos) { om0[r] = 1.f; p0[r] = 0.f; } if (key + 32 >= qpos) { om1[r] = 1.f; p1[r] = 0.f; } }
;             }
;             float gs[8], og[8];
; #pragma unroll
;             for (int g = 0; g < 4; ++g) { gs[g] = (om0[4 * g] * om0[4 * g + 1]) * (om0[4 * g + 2] * om0[4 * g + 3]); gs[4 + g] = (om1[4 * g] * om1[4 * g + 1]) * (om1[4 * g + 2] * om1[4 * g + 3]); }
; #pragma unroll
;             for (int g = 0; g < 8; ++g) og[g] = xother32(gs[g], hi);
;             float suf = lrun;
; #pragma unroll
;             for (int g = 7; g >= 0; --g) {
;                 const float T = suf * (hi == 0 ? og[g] : 1.f);
;                 f32x16& om = (g < 4) ? om0 : om1; f32x16& pp = (g < 4) ? p0 : p1; const int b = 4 * (g & 3);
;                 const float l3 = T, l2 = l3 * om[b + 3], l1 = l2 * om[b + 2], l0 = l1 * om[b + 1];
;                 pp[b + 3] *= l3; pp[b + 2] *= l2; pp[b + 1] *= l1; pp[b] *= l0;
;                 suf *= gs[g] * og[g];
;             }
;             lrun = suf;
;         }
;         pf[0] = packp(p0, 0); pf[1] = packp(p0, 8); pf[2] = packp(p1, 0); pf[3] = packp(p1, 8);
.LBB0_1368:
	v_max_f32_e32 v32, v49, v49
	v_max_f32_e32 v33, v48, v48
	v_max_f32_e32 v32, v33, v32
	v_max_f32_e32 v33, v51, v51
	v_max_f32_e32 v34, v50, v50
	v_max_f32_e32 v33, v34, v33
	v_max_f32_e32 v34, v55, v55
	v_max_f32_e32 v35, v54, v54
	v_max_f32_e32 v34, v35, v34
	v_max_f32_e32 v35, v57, v57
	v_max_f32_e32 v38, v56, v56
	v_max_f32_e32 v35, v38, v35
	v_max_f32_e32 v38, v59, v59
	v_max_f32_e32 v39, v58, v58
	v_max_f32_e32 v38, v39, v38
	v_max_f32_e32 v39, v63, v63
	v_max_f32_e32 v42, v62, v62
	v_max_f32_e32 v39, v42, v39
	v_max3_f32 v34, v52, v53, v34
	v_max3_f32 v39, v60, v61, v39
	v_max3_f32 v32, v32, v33, v34
	v_max3_f32 v33, v35, v38, v39
	v_max_f32_e32 v34, v41, v41
	v_max_f32_e32 v35, v40, v40
	v_max_f32_e32 v34, v35, v34
	v_max_f32_e32 v35, v47, v47
	v_max_f32_e32 v38, v46, v46
	v_max_f32_e32 v35, v38, v35
	v_max_f32_e32 v38, v133, v133
	v_max_f32_e32 v39, v132, v132
	v_max_f32_e32 v38, v39, v38
	v_max_f32_e32 v39, v131, v131
	v_max_f32_e32 v42, v130, v130
	v_max_f32_e32 v39, v42, v39
	v_max_f32_e32 v42, v127, v127
	v_max_f32_e32 v43, v126, v126
	v_max_f32_e32 v42, v43, v42
	v_max3_f32 v42, v128, v129, v42
	v_max3_f32 v34, v36, v37, v34
	v_max3_f32 v35, v44, v45, v35
	v_max3_f32 v38, v38, v39, v42
	v_max3_f32 v34, v34, v35, v38
	v_max3_f32 v32, v32, v33, v34
	v_mov_b32_e32 v33, v32
	s_nop 1
	v_permlane32_swap_b32_e32 v32, v33
	v_max3_f32 v143, v142, v32, v33
	v_sub_f32_e32 v32, v48, v143
	v_exp_f32_e32 v33, v32
	v_sub_f32_e32 v32, v36, v143
	v_sub_f32_e32 v34, v49, v143
	v_sub_f32_e32 v36, v50, v143
	v_exp_f32_e32 v35, v34
	v_sub_f32_e32 v34, v37, v143
	v_exp_f32_e32 v37, v36
	v_sub_f32_e32 v36, v40, v143
	v_sub_f32_e32 v38, v51, v143
	v_sub_f32_e32 v40, v52, v143
	v_exp_f32_e32 v39, v38
	v_sub_f32_e32 v38, v41, v143
	v_exp_f32_e32 v41, v40
	v_sub_f32_e32 v40, v44, v143
	v_sub_f32_e32 v42, v53, v143
	v_sub_f32_e32 v44, v54, v143
	v_exp_f32_e32 v43, v42
	v_sub_f32_e32 v42, v45, v143
	v_exp_f32_e32 v45, v44
	v_sub_f32_e32 v44, v46, v143
	v_sub_f32_e32 v46, v55, v143
	v_exp_f32_e32 v32, v32
	v_exp_f32_e32 v34, v34
	v_exp_f32_e32 v36, v36
	v_exp_f32_e32 v38, v38
	v_exp_f32_e32 v49, v46
	v_sub_f32_e32 v46, v47, v143
	v_exp_f32_e32 v40, v40
	v_exp_f32_e32 v42, v42
	v_exp_f32_e32 v44, v44
	v_exp_f32_e32 v48, v46
	v_sub_f32_e32 v46, v56, v143
	v_sub_f32_e32 v50, v57, v143
	v_sub_f32_e32 v52, v58, v143
	v_sub_f32_e32 v54, v59, v143
	v_exp_f32_e32 v47, v46
	v_sub_f32_e32 v46, v132, v143
	v_exp_f32_e32 v51, v50
	v_sub_f32_e32 v50, v133, v143
	v_exp_f32_e32 v53, v52
	v_sub_f32_e32 v52, v130, v143
	v_exp_f32_e32 v55, v54
	v_sub_f32_e32 v54, v131, v143
	v_sub_f32_e32 v56, v60, v143
	v_sub_f32_e32 v58, v61, v143
	v_sub_f32_e32 v60, v62, v143
	v_sub_f32_e32 v62, v63, v143
	v_exp_f32_e32 v46, v46
	v_exp_f32_e32 v50, v50
	v_exp_f32_e32 v52, v52
	v_exp_f32_e32 v54, v54
	v_exp_f32_e32 v57, v56
	v_sub_f32_e32 v56, v128, v143
	v_exp_f32_e32 v59, v58
	v_sub_f32_e32 v58, v129, v143
	v_exp_f32_e32 v61, v60
	v_sub_f32_e32 v60, v126, v143
	v_exp_f32_e32 v63, v62
	v_sub_f32_e32 v62, v127, v143
	v_exp_f32_e32 v56, v56
	v_exp_f32_e32 v58, v58
	v_exp_f32_e32 v60, v60
	v_exp_f32_e32 v62, v62
	v_pk_add_f32 v[126:127], v[32:33], v[34:35]
	v_pk_add_f32 v[130:131], v[36:37], v[38:39]
	v_pk_add_f32 v[132:133], v[44:45], v[48:49]
	v_pk_add_f32 v[126:127], v[126:127], v[130:131]
	v_pk_add_f32 v[130:131], v[40:41], v[42:43]
	v_sub_f32_e32 v142, v142, v143
	v_pk_add_f32 v[130:131], v[130:131], v[132:133]
	v_pk_add_f32 v[132:133], v[52:53], v[54:55]
	v_pk_add_f32 v[126:127], v[126:127], v[130:131]
	v_pk_add_f32 v[130:131], v[46:47], v[50:51]
	v_pk_add_f32 v[144:145], v[60:61], v[62:63]
	v_pk_add_f32 v[130:131], v[130:131], v[132:133]
	v_pk_add_f32 v[132:133], v[56:57], v[58:59]
	v_exp_f32_e32 v128, v142
	v_pk_add_f32 v[132:133], v[132:133], v[144:145]
	v_mov_b32_e32 v142, v143
	v_pk_add_f32 v[130:131], v[130:131], v[132:133]
	v_pk_mul_f32 v[30:31], v[30:31], v[128:129] op_sel_hi:[1,0]
	v_pk_add_f32 v[126:127], v[126:127], v[130:131]
	v_pk_mul_f32 v[28:29], v[28:29], v[128:129] op_sel_hi:[1,0]
	v_add_f32_e32 v126, v126, v127
	v_fmac_f32_e32 v126, v141, v128
	v_pk_mul_f32 v[26:27], v[26:27], v[128:129] op_sel_hi:[1,0]
	v_pk_mul_f32 v[24:25], v[24:25], v[128:129] op_sel_hi:[1,0]
	v_pk_mul_f32 v[22:23], v[22:23], v[128:129] op_sel_hi:[1,0]
	v_pk_mul_f32 v[20:21], v[20:21], v[128:129] op_sel_hi:[1,0]
	v_pk_mul_f32 v[18:19], v[18:19], v[128:129] op_sel_hi:[1,0]
	v_pk_mul_f32 v[16:17], v[16:17], v[128:129] op_sel_hi:[1,0]
	v_pk_mul_f32 v[14:15], v[14:15], v[128:129] op_sel_hi:[1,0]
	v_pk_mul_f32 v[12:13], v[12:13], v[128:129] op_sel_hi:[1,0]
	v_pk_mul_f32 v[10:11], v[10:11], v[128:129] op_sel_hi:[1,0]
	v_pk_mul_f32 v[8:9], v[8:9], v[128:129] op_sel_hi:[1,0]
	v_pk_mul_f32 v[6:7], v[6:7], v[128:129] op_sel_hi:[1,0]
	v_pk_mul_f32 v[4:5], v[4:5], v[128:129] op_sel_hi:[1,0]
	v_pk_mul_f32 v[2:3], v[2:3], v[128:129] op_sel_hi:[1,0]
	v_pk_mul_f32 v[0:1], v[0:1], v[128:129] op_sel_hi:[1,0]
	v_cvt_pk_bf16_f32 v128, v33, v35
	v_cvt_pk_bf16_f32 v129, v37, v39
	v_cvt_pk_bf16_f32 v130, v41, v43
	v_cvt_pk_bf16_f32 v131, v45, v49
	v_cvt_pk_bf16_f32 v144, v47, v51
	v_cvt_pk_bf16_f32 v145, v53, v55
	v_cvt_pk_bf16_f32 v146, v57, v59
	v_cvt_pk_bf16_f32 v147, v61, v63
	v_cvt_pk_bf16_f32 v32, v32, v34
	v_cvt_pk_bf16_f32 v33, v36, v38
	v_cvt_pk_bf16_f32 v34, v40, v42
	v_cvt_pk_bf16_f32 v35, v44, v48
	v_add_u32_e32 v44, v135, v136
	v_cvt_pk_bf16_f32 v36, v46, v50
	v_cvt_pk_bf16_f32 v37, v52, v54
	v_cvt_pk_bf16_f32 v38, v56, v58
	v_cvt_pk_bf16_f32 v39, v60, v62
	s_waitcnt lgkmcnt(0)
	ds_read_b64_tr_b16 v[226:227], v44 offset:20480
	ds_read_b64_tr_b16 v[228:229], v44 offset:20992
	v_mov_b32_e32 v141, v126
	v_mfma_f32_32x32x16_bf16 v[16:31], v[196:199], v[128:131], v[16:31]
	v_mfma_f32_32x32x16_bf16 v[16:31], v[200:203], v[144:147], v[16:31]
	v_mfma_f32_32x32x16_bf16 v[16:31], v[204:207], v[32:35], v[16:31]
	v_mfma_f32_32x32x16_bf16 v[16:31], v[210:213], v[36:39], v[16:31]
	v_mfma_f32_32x32x16_bf16 v[0:15], v[214:217], v[128:131], v[0:15]
	v_mfma_f32_32x32x16_bf16 v[0:15], v[218:221], v[144:147], v[0:15]
	v_mfma_f32_32x32x16_bf16 v[0:15], v[222:225], v[32:35], v[0:15]
	s_waitcnt lgkmcnt(0)
	v_mfma_f32_32x32x16_bf16 v[0:15], v[226:229], v[36:39], v[0:15]

; __device__ __forceinline__ s16x4 vtr(lds_cptr p) { return __builtin_bit_cast(s16x4, __builtin_amdgcn_ds_read_tr16_b64_v4i16((ATT_LAS s16x4*)p)); }
; template <int KEYS> __device__ __forceinline__ void pv_tile(f32x16 (&o)[2], lds_cptr vbase, const bf16x8 (&pf)[KEYS / 16], int lane) {
;     const int hi = lane >> 5, li = lane & 15;
;     lds_cptr vp = vbase + (4 * hi + (li >> 2)) * 64 + ((lane >> 4) & 1) * 32 + (lane & 3) * 8;
; #pragma unroll
;     for (int d0 = 0; d0 < 2; ++d0)
; #pragma unroll
;         for (int ks = 0; ks < KEYS / 16; ++ks) {
;             const s16x4 lo = vtr(vp + d0 * (KEYS * 64) + ks * 1024), hh = vtr(vp + d0 * (KEYS * 64) + ks * 1024 + 512);
; template <int DK, int MODE>
; __device__ __forceinline__ void attn_unit(const bf16_t* Q, int ldq, const bf16_t* K, int ldk, const bf16_t* V, int ldv, bf16_t* O, int ldo, int qb, char* shm, float sc) {
;     ...
;     auto att_compute = [&](int it, int tt, char* buf) __attribute__((always_inline)) {
;         const int kbase = tt * 64;
;         bool active = !(kbase > qb * 256 + wid * 32 + 31);
;         if (MODE == 1) active = active && (wminR < SB_SAT);
;         if (active) {
;         f32x16 p0 = f32x16{}, p1 = f32x16{};
;         const char* kp = buf + r32 * L::KS + hi * 16;
; #pragma unroll
;         for (int s = 0; s < NS; ++s) {
;             const bf16x8 a0 = *(const bf16x8*)(kp + s * 32), a1 = *(const bf16x8*)(kp + 32 * L::KS + s * 32);
;             p0 = __builtin_amdgcn_mfma_f32_32x32x16_bf16(a0, qf[s], p0, 0, 0, 0);
;             p1 = __builtin_amdgcn_mfma_f32_32x32x16_bf16(a1, qf[s], p1, 0, 0, 0);
;         }
;         const bool diag = (kbase + 63 >= qb * 256 + wid * 32);
.LBB0_1373:
	s_or_b64 exec, exec, s[28:29]
	v_lshl_add_u64 v[32:33], s[0:1], 0, v[118:119]
	v_lshlrev_b64 v[32:33], 10, v[32:33]
	v_lshl_add_u64 v[32:33], v[122:123], 0, v[32:33]
	global_load_dwordx4 v[108:111], v[32:33], off
	s_add_i32 s0, s31, 1
	s_cmp_gt_i32 s0, s30
	s_cbranch_scc1 .LBB0_1360
	ds_read_b128 v[148:151], v140 offset:21504
	ds_read_b128 v[152:155], v140 offset:28160
	ds_read_b128 v[156:159], v140 offset:21536
	ds_read_b128 v[160:163], v140 offset:28192
	ds_read_b128 v[164:167], v140 offset:21568
	ds_read_b128 v[168:171], v140 offset:28224
	ds_read_b128 v[172:175], v140 offset:21600
	ds_read_b128 v[176:179], v140 offset:28256
	ds_read_b128 v[180:183], v140 offset:21632
	ds_read_b128 v[184:187], v140 offset:28288
	ds_read_b128 v[188:191], v140 offset:21664
	ds_read_b128 v[192:195], v140 offset:28320
	s_add_i32 s0, s31, 64
	s_cmp_lt_i32 s0, s9
	s_waitcnt lgkmcnt(11)
	v_mfma_f32_32x32x16_bf16 v[48:63], v[148:151], v[64:67], 0
	s_waitcnt lgkmcnt(10)
	v_mfma_f32_32x32x16_bf16 v[32:47], v[152:155], v[64:67], 0
	s_waitcnt lgkmcnt(9)
	v_mfma_f32_32x32x16_bf16 v[48:63], v[156:159], v[68:71], v[48:63]
	s_waitcnt lgkmcnt(8)
	v_mfma_f32_32x32x16_bf16 v[32:47], v[160:163], v[68:71], v[32:47]
	s_waitcnt lgkmcnt(7)
	v_mfma_f32_32x32x16_bf16 v[48:63], v[164:167], v[72:75], v[48:63]
	s_waitcnt lgkmcnt(6)
	v_mfma_f32_32x32x16_bf16 v[32:47], v[168:171], v[72:75], v[32:47]
	s_waitcnt lgkmcnt(5)
	v_mfma_f32_32x32x16_bf16 v[48:63], v[172:175], v[76:79], v[48:63]
	s_waitcnt lgkmcnt(4)
	v_mfma_f32_32x32x16_bf16 v[32:47], v[176:179], v[76:79], v[32:47]
	s_waitcnt lgkmcnt(3)
	v_mfma_f32_32x32x16_bf16 v[48:63], v[180:183], v[80:83], v[48:63]
	s_waitcnt lgkmcnt(2)
	v_mfma_f32_32x32x16_bf16 v[32:47], v[184:187], v[80:83], v[32:47]
	s_waitcnt lgkmcnt(1)
	v_mfma_f32_32x32x16_bf16 v[48:63], v[188:191], v[84:87], v[48:63]
	s_waitcnt lgkmcnt(0)
	v_mfma_f32_32x32x16_bf16 v[32:47], v[192:195], v[84:87], v[32:47]
	v_add_u32_e32 v230, v135, v136
	ds_read_b64_tr_b16 v[196:197], v230 offset:34816
	ds_read_b64_tr_b16 v[198:199], v230 offset:35328
	ds_read_b64_tr_b16 v[200:201], v230 offset:35840
	ds_read_b64_tr_b16 v[202:203], v230 offset:36352
	ds_read_b64_tr_b16 v[204:205], v230 offset:36864
	ds_read_b64_tr_b16 v[206:207], v230 offset:37376
	ds_read_b64_tr_b16 v[210:211], v230 offset:37888
	ds_read_b64_tr_b16 v[212:213], v230 offset:38400
	ds_read_b64_tr_b16 v[214:215], v230 offset:38912
	ds_read_b64_tr_b16 v[216:217], v230 offset:39424
	ds_read_b64_tr_b16 v[218:219], v230 offset:39936
	ds_read_b64_tr_b16 v[220:221], v230 offset:40448
	ds_read_b64_tr_b16 v[222:223], v230 offset:40960
	ds_read_b64_tr_b16 v[224:225], v230 offset:41472
	s_nop 9
	v_mul_f32_e64 v62, v62, s24
	v_mul_f32_e64 v63, v63, s24
	v_mul_f32_e64 v60, v60, s24
	v_mul_f32_e64 v61, v61, s24
	v_mul_f32_e64 v58, v58, s24
	v_mul_f32_e64 v59, v59, s24
	v_pk_mul_f32 v[56:57], v[56:57], s[24:25] op_sel_hi:[1,0]
	v_pk_mul_f32 v[54:55], v[54:55], s[24:25] op_sel_hi:[1,0]
	v_pk_mul_f32 v[52:53], v[52:53], s[24:25] op_sel_hi:[1,0]
	v_pk_mul_f32 v[50:51], v[50:51], s[24:25] op_sel_hi:[1,0]
	v_pk_mul_f32 v[48:49], v[48:49], s[24:25] op_sel_hi:[1,0]
	v_pk_mul_f32 v[126:127], v[46:47], s[24:25] op_sel_hi:[1,0]
	v_pk_mul_f32 v[128:129], v[44:45], s[24:25] op_sel_hi:[1,0]
	v_pk_mul_f32 v[130:131], v[42:43], s[24:25] op_sel_hi:[1,0]
	v_pk_mul_f32 v[132:133], v[40:41], s[24:25] op_sel_hi:[1,0]
	v_pk_mul_f32 v[46:47], v[38:39], s[24:25] op_sel_hi:[1,0]
	v_pk_mul_f32 v[44:45], v[36:37], s[24:25] op_sel_hi:[1,0]
	v_pk_mul_f32 v[40:41], v[34:35], s[24:25] op_sel_hi:[1,0]
	v_pk_mul_f32 v[36:37], v[32:33], s[24:25] op_sel_hi:[1,0]
	s_cbranch_scc1 .LBB0_1359
; __device__ __forceinline__ int crow(int r, int hi) { return (r & 3) + 8 * (r >> 2) + 4 * hi; }
; template <int DK, int MODE>
; __device__ __forceinline__ void attn_unit(const bf16_t* Q, int ldq, const bf16_t* K, int ldk, const bf16_t* V, int ldv, bf16_t* O, int ldo, int qb, char* shm, float sc) {
;     ...
;             if (diag) {
; #pragma unroll
;                 for (int r = 0; r < 16; ++r) { const int key = kbase + crow(r, hi); if (key > qpos) p0[r] = -INFINITY; if (key + 32 > qpos) p1[r] = -INFINITY; }
;             }
	v_add_u32_e32 v32, s31, v134
	v_add_u32_e32 v34, 33, v32
	v_add_u32_e32 v33, 1, v32
	v_cmp_le_i32_e32 vcc, v34, v112
	s_nop 1
	v_cndmask_b32_e32 v36, v243, v36, vcc
	v_cmp_lt_i32_e32 vcc, v33, v112
	s_nop 1
	v_cndmask_b32_e32 v49, v243, v49, vcc
	v_cmp_le_i32_e32 vcc, v33, v112
	v_add_u32_e32 v33, 34, v32
	s_nop 0
	v_cndmask_b32_e32 v48, v243, v48, vcc
	v_cmp_le_i32_e32 vcc, v33, v112
	v_add_u32_e32 v33, 3, v32
	s_nop 0
	v_cndmask_b32_e32 v37, v243, v37, vcc
	v_cmp_le_i32_e32 vcc, v33, v112
	v_add_u32_e32 v33, 35, v32
	s_nop 0
	v_cndmask_b32_e32 v50, v243, v50, vcc
	v_cmp_le_i32_e32 vcc, v33, v112
	v_add_u32_e32 v33, 4, v32
	s_nop 0
	v_cndmask_b32_e32 v40, v243, v40, vcc
	v_cmp_le_i32_e32 vcc, v33, v112
	v_add_u32_e32 v33, 36, v32
	s_nop 0
	v_cndmask_b32_e32 v51, v243, v51, vcc
	v_cmp_le_i32_e32 vcc, v33, v112
	v_add_u32_e32 v33, 9, v32
	s_nop 0
	v_cndmask_b32_e32 v41, v243, v41, vcc
	v_cmp_le_i32_e32 vcc, v33, v112
	v_add_u32_e32 v33, 41, v32
	s_nop 0
	v_cndmask_b32_e32 v52, v243, v52, vcc
	v_cmp_le_i32_e32 vcc, v33, v112
	v_add_u32_e32 v33, 10, v32
	s_nop 0
	v_cndmask_b32_e32 v44, v243, v44, vcc
	v_cmp_le_i32_e32 vcc, v33, v112
	v_add_u32_e32 v33, 42, v32
	s_nop 0
	v_cndmask_b32_e32 v53, v243, v53, vcc
	v_cmp_le_i32_e32 vcc, v33, v112
	v_add_u32_e32 v33, 11, v32
	s_nop 0
	v_cndmask_b32_e32 v45, v243, v45, vcc
	v_cmp_le_i32_e32 vcc, v33, v112
	v_add_u32_e32 v33, 43, v32
	s_nop 0
	v_cndmask_b32_e32 v54, v243, v54, vcc
	v_cmp_le_i32_e32 vcc, v33, v112
	v_add_u32_e32 v33, 12, v32
	s_nop 0
	v_cndmask_b32_e32 v46, v243, v46, vcc
	v_cmp_le_i32_e32 vcc, v33, v112
	v_add_u32_e32 v33, 44, v32
	s_nop 0
	v_cndmask_b32_e32 v55, v243, v55, vcc
	v_cmp_le_i32_e32 vcc, v33, v112
	v_add_u32_e32 v33, 17, v32
	s_nop 0
	v_cndmask_b32_e32 v47, v243, v47, vcc
	v_cmp_le_i32_e32 vcc, v33, v112
	v_add_u32_e32 v33, 49, v32
	s_nop 0
	v_cndmask_b32_e32 v56, v243, v56, vcc
	v_cmp_le_i32_e32 vcc, v33, v112
	v_add_u32_e32 v33, 18, v32
	s_nop 0
	v_cndmask_b32_e32 v132, v243, v132, vcc
	v_cmp_le_i32_e32 vcc, v33, v112
	v_add_u32_e32 v33, 50, v32
	s_nop 0
	v_cndmask_b32_e32 v57, v243, v57, vcc
	v_cmp_le_i32_e32 vcc, v33, v112
	v_add_u32_e32 v33, 19, v32
	s_nop 0
	v_cndmask_b32_e32 v133, v243, v133, vcc
	v_cmp_le_i32_e32 vcc, v33, v112
	v_add_u32_e32 v33, 51, v32
	s_nop 0
	v_cndmask_b32_e32 v58, v243, v58, vcc
	v_cmp_le_i32_e32 vcc, v33, v112
	v_add_u32_e32 v33, 20, v32
	s_nop 0
	v_cndmask_b32_e32 v130, v243, v130, vcc
	v_cmp_le_i32_e32 vcc, v33, v112
	v_add_u32_e32 v33, 52, v32
	s_nop 0
	v_cndmask_b32_e32 v59, v243, v59, vcc
	v_cmp_le_i32_e32 vcc, v33, v112
	v_add_u32_e32 v33, 25, v32
	s_nop 0
	v_cndmask_b32_e32 v131, v243, v131, vcc
	v_cmp_le_i32_e32 vcc, v33, v112
	v_add_u32_e32 v33, 57, v32
	s_nop 0
	v_cndmask_b32_e32 v60, v243, v60, vcc
	v_cmp_le_i32_e32 vcc, v33, v112
	v_add_u32_e32 v33, 26, v32
	s_nop 0
	v_cndmask_b32_e32 v128, v243, v128, vcc
	v_cmp_le_i32_e32 vcc, v33, v112
	v_add_u32_e32 v33, 58, v32
	s_nop 0
	v_cndmask_b32_e32 v61, v243, v61, vcc
	v_cmp_le_i32_e32 vcc, v33, v112
	v_add_u32_e32 v33, 27, v32
	s_nop 0
	v_cndmask_b32_e32 v129, v243, v129, vcc
	v_cmp_le_i32_e32 vcc, v33, v112
	v_add_u32_e32 v33, 59, v32
	s_nop 0
	v_cndmask_b32_e32 v62, v243, v62, vcc
	v_cmp_le_i32_e32 vcc, v33, v112
	v_add_u32_e32 v33, 28, v32
	v_add_u32_e32 v32, 60, v32
	v_cndmask_b32_e32 v126, v243, v126, vcc
	v_cmp_le_i32_e32 vcc, v33, v112
	s_nop 1
	v_cndmask_b32_e32 v63, v243, v63, vcc
	v_cmp_le_i32_e32 vcc, v32, v112
	s_nop 1
	v_cndmask_b32_e32 v127, v243, v127, vcc
	s_branch .LBB0_1359
